# post-P0 cooperative-groups grid.sync replaced by the XCD-hierarchical barrier (same release/acquire protocol as the other 14 seams)
# speedup vs baseline: 1.0501x; 1.0070x over previous
.LBB0_118:
	s_load_dword s0, s[80:81], 0x90
	s_cmpk_lt_i32 s73, 0xc0
	s_cselect_b64 s[2:3], -1, 0
	s_mul_i32 s1, s77, s76
	v_writelane_b32 v255, s2, 4
	s_cmpk_lt_i32 s73, 0x100
	s_waitcnt lgkmcnt(0)
	s_mul_i32 s77, s1, s0
	v_writelane_b32 v255, s3, 5
	s_cselect_b64 s[0:1], -1, 0
	v_writelane_b32 v255, s0, 6
	s_cmp_lt_i32 s73, 64
	s_mov_b32 s85, 0
	v_writelane_b32 v255, s1, 7
	s_cselect_b64 s[0:1], -1, 0
	v_writelane_b32 v255, s0, 8
	s_mov_b64 s[12:13], -1
	s_movk_i32 s74, 0x61
	v_writelane_b32 v255, s1, 9
	s_lshl_b32 s0, s73, 1
	s_cmpk_lt_i32 s0, 0x200
	v_writelane_b32 v255, s0, 10
	s_cselect_b64 s[0:1], -1, 0
	v_writelane_b32 v255, s0, 11
	s_lshl_b32 s70, s76, 9
	s_lshl_b32 s71, s76, 12
	v_writelane_b32 v255, s1, 12
	s_lshl_b32 s0, s76, 1
	v_writelane_b32 v255, s0, 13
	s_and_b32 s0, s73, 7
	v_writelane_b32 v255, s0, 14
	s_and_b32 s0, s73, -8
	v_writelane_b32 v255, s0, 15
	s_lshl_b32 s0, s73, 5
	v_writelane_b32 v255, s0, 16
	s_lshl_b32 s0, s73, 12
	v_writelane_b32 v255, s0, 17
	s_add_i32 s0, 0, 0x27ff0
	v_writelane_b32 v255, s0, 18
	s_add_i32 s0, 0, 0x27ff4
	v_writelane_b32 v255, s0, 19
	s_add_i32 s0, 0, 0x12700
	v_writelane_b32 v255, s0, 20
	s_add_i32 s0, 0, 0x1ce0
	v_writelane_b32 v255, s0, 21
	s_add_i32 s0, 0, 0x3de0
	v_writelane_b32 v255, s0, 22
	v_writelane_b32 v255, s80, 23
	s_lshl_b32 s94, s76, 5
	s_movk_i32 s75, 0x2000
	v_writelane_b32 v255, s81, 24
	v_writelane_b32 v255, s68, 25
	v_mov_b32_e32 v189, 0
	s_mov_b64 s[86:87], 0x80000
	v_writelane_b32 v255, s69, 26
	v_writelane_b32 v255, s77, 27
	v_writelane_b32 v255, s70, 28
	v_writelane_b32 v255, s71, 29
	s_mov_b64 s[88:89], 0x80
	v_mov_b32_e32 v233, 0x358637bd
	s_mov_b32 s96, 0x800000
	s_movk_i32 s97, 0x7ff
	s_movk_i32 s82, 0x1000
	s_movk_i32 s83, 0x3ff
	v_mov_b32_e32 v241, 0x1000
	v_mov_b32_e32 v253, 0x2000
	v_mov_b32_e32 v242, 1
	s_movk_i32 s95, 0x210
	s_movk_i32 s72, 0xffd
	s_movk_i32 s78, 0xfff
	v_mov_b64_e32 v[190:191], 0xff
	v_mov_b64_e32 v[192:193], 0x100
	v_mbcnt_hi_u32_b32 v238, -1, v1
	v_mov_b32_e32 v239, 0xff800000
	s_mov_b64 s[92:93], 0x40000
	s_mov_b32 s30, s85
	v_writelane_b32 v255, s73, 30
	s_cmpk_lt_u32 s73, 0x80
	s_cselect_b32 s0, 32, 40
	s_mov_b32 s3, 0x8194000
	s_cselect_b32 s2, s3, 0x1c194000
	s_add_u32 s0, s80, s0
	s_addc_u32 s1, s81, 0
	s_load_dwordx2 s[98:99], s[0:1], 0x0
	s_load_dwordx2 s[100:101], s[80:81], 0x78
	s_lshl_b32 s0, s73, 21
	s_and_b32 s0, s0, 0xf000000
	s_and_b32 s1, s73, 7
	s_mul_i32 s1, s1, 0x1ff000
	s_add_u32 s0, s0, s1
	s_waitcnt lgkmcnt(0)
	s_add_u32 s98, s98, s0
	s_addc_u32 s99, s99, 0
	s_add_u32 s98, s98, 0x8000
	s_addc_u32 s99, s99, 0
	s_add_u32 s100, s100, s2
	s_addc_u32 s101, s101, 0
	s_add_u32 s100, s100, s0
	s_addc_u32 s101, s101, 0
	v_writelane_b32 v255, s98, 49
	v_writelane_b32 v255, s99, 50
	v_writelane_b32 v255, s100, 51
	v_writelane_b32 v255, s101, 52
	s_mov_b64 s[0:1], s[80:81]
	s_getreg_b32 s2, hwreg(HW_REG_XCC_ID, 0, 4)
	s_waitcnt vmcnt(0)
	s_barrier
	s_and_saveexec_b64 s[4:5], s[68:69]
	s_cbranch_execz .Lgsx_1258
	s_load_dwordx2 s[6:7], s[0:1], 0x80
	v_readlane_b32 s0, v255, 18
	s_waitcnt vmcnt(0) expcnt(0) lgkmcnt(0)
	s_and_b32 s33, s2, 15
	v_mov_b32_e32 v0, s0
	ds_read_b32 v2, v0
	v_readlane_b32 s0, v255, 19
	s_waitcnt lgkmcnt(0)
	v_cmp_ne_u32_e32 vcc, 0, v2
	v_mov_b32_e32 v0, s0
	ds_read_b32 v0, v0
	s_cbranch_vccnz .Lgsx_1222
	s_add_u32 s2, s6, 0x1f3c8500
	s_addc_u32 s3, s7, 0
	s_add_u32 s8, s6, 0x1f3c8700
	s_addc_u32 s9, s7, 0
	s_add_u32 s10, s6, 0x1f3c8800
	s_addc_u32 s11, s7, 0
	s_add_u32 s12, s6, 0x1f3c8900
	s_addc_u32 s13, s7, 0
	s_add_u32 s14, s6, 0x1f3c8a00
	s_addc_u32 s15, s7, 0
	s_add_u32 s16, s6, 0x1f3c8b00
	s_addc_u32 s17, s7, 0
	s_add_u32 s18, s6, 0x1f3c8c00
	s_addc_u32 s19, s7, 0
	s_add_u32 s20, s6, 0x1f3c8d00
	s_addc_u32 s21, s7, 0
	s_add_u32 s22, s6, 0x1f3c8e00
	s_addc_u32 s23, s7, 0
	s_add_u32 s24, s6, 0x1f3c8f00
	s_addc_u32 s25, s7, 0
	s_add_u32 s26, s6, 0x1f3c9000
	s_addc_u32 s27, s7, 0
	s_add_u32 s28, s6, 0x1f3c9100
	s_addc_u32 s29, s7, 0
	s_add_u32 s30, s6, 0x1f3c9200
	s_addc_u32 s31, s7, 0
	s_add_u32 s34, s6, 0x1f3c9300
	s_addc_u32 s35, s7, 0
	s_add_u32 s36, s6, 0x1f3c9400
	s_addc_u32 s37, s7, 0
	s_add_u32 s38, s6, 0x1f3c9500
	s_addc_u32 s39, s7, 0
	s_add_u32 s40, s6, 0x1f3c9600
	s_addc_u32 s41, s7, 0
	s_mov_b32 s46, 1
	s_branch .Lgsx_1210

.Lgsx_1258:
	s_or_b64 exec, exec, s[4:5]
	s_mov_b64 s[0:1], s[80:81]
	s_waitcnt lgkmcnt(0)
	s_barrier
	s_mov_b64 s[12:13], -1
	s_mov_b32 s30, s85
	s_branch .LBB0_131
